# adds software-pipelined phase-H context small GEMM (operand loads 5 k-steps ahead, counted vmcnt) on top of previous version
# speedup vs baseline: 1.0131x; 1.0022x over previous
.LBB0_1464:
	s_and_b32 s16, s13, 0xffffffe0
	s_add_i32 s17, s16, 0x4000
	v_mov_b32_e32 v0, 0x1600
	v_mad_i64_i32 v[34:35], s[18:19], s17, v0, v[42:43]
	s_mov_b64 s[18:19], 0x16000
	s_and_b32 s15, s14, 15
	v_lshl_add_u64 v[38:39], v[34:35], 0, s[18:19]
	s_bfe_u32 s18, s14, 0x20002
	s_lshl_b32 s15, s15, 6
	s_mul_i32 s18, s18, 44
	s_add_i32 s19, s18, s2
	v_and_or_b32 v0, s15, 64, v44
	s_bfe_u32 s17, s14, 0x10001
	s_lshl_b32 s19, s19, 1
	v_lshrrev_b32_e32 v100, 3, v0
	s_or_b32 s20, s19, s17
	v_or_b32_e32 v0, s3, v100
	s_ashr_i32 s21, s20, 31
	v_lshl_or_b32 v0, v0, 10, v45
	v_or_b32_e32 v101, 4, v100
	s_lshl_b64 s[20:21], s[20:21], 14
	v_or_b32_e32 v71, v0, v46
	v_bitop3_b32 v69, v0, 32, v47 bitop3:0x36
	v_or_b32_e32 v0, s3, v101
	s_add_u32 s20, s4, s20
	v_lshl_or_b32 v0, v0, 10, v45
	s_addc_u32 s21, s5, s21
	v_or_b32_e32 v70, v0, v46
	v_bitop3_b32 v68, v0, 32, v48 bitop3:0x36
	v_and_b32_e32 v116, 15, v220
	v_bfe_u32 v117, v220, 4, 2
	v_bfe_u32 v118, v116, 2, 1
	v_lshlrev_b32_e32 v118, 11, v118
	v_lshrrev_b32_e32 v120, 3, v116
	v_lshl_or_b32 v118, v120, 8, v118
	v_and_b32_e32 v120, 3, v116
	v_lshl_or_b32 v118, v120, 6, v118
	v_lshl_or_b32 v84, v117, 4, v118
	v_xor_b32_e32 v85, 32, v84
	v_add_u32_e32 v85, 0x200, v85
	v_add_u32_e32 v86, 0x1000, v84
	v_add_u32_e32 v87, 0x1000, v85
	v_readfirstlane_b32 s20, v220
	s_and_b32 s17, s14, 15
	s_lshr_b32 s100, s17, 2
	s_mul_i32 s100, s100, 0x160000
	s_bfe_u32 s21, s17, 0x10001
	s_lshl_b32 s21, s21, 14
	s_add_i32 s100, s100, s21
	s_and_b32 s21, s17, 1
	s_lshl_b32 s21, s21, 13
	s_add_i32 s100, s100, s21
	s_lshr_b32 s20, s20, 6
	s_mul_i32 s20, s20, 11
	s_lshr_b32 s21, s20, 1
	s_lshl_b32 s21, s21, 15
	s_add_i32 s100, s100, s21
	s_and_b32 s21, s20, 1
	s_lshl_b32 s17, s21, 10
	s_add_i32 s100, s100, s17
	s_add_u32 s18, s4, s100
	s_addc_u32 s19, s5, 0
	s_movk_i32 s20, 0x400
	s_movk_i32 s17, 0x7c00
	s_cmp_eq_u32 s21, 0
	s_cselect_b32 s101, s20, s17
	s_cselect_b32 s17, s17, s20
	global_load_dwordx4 v[72:75], v[34:35], off offset:0
	global_load_dwordx4 v[76:79], v[38:39], off offset:0
	global_load_dwordx4 v[80:83], v84, s[18:19]
	global_load_dwordx4 v[88:91], v85, s[18:19]
	global_load_dwordx4 v[92:95], v86, s[18:19]
	global_load_dwordx4 v[96:99], v87, s[18:19]
	s_add_u32 s18, s18, s101
	s_addc_u32 s19, s19, 0
	global_load_dwordx4 v[100:103], v[34:35], off offset:64
	global_load_dwordx4 v[104:107], v[38:39], off offset:64
	global_load_dwordx4 v[108:111], v84, s[18:19]
	global_load_dwordx4 v[112:115], v85, s[18:19]
	global_load_dwordx4 v[124:127], v86, s[18:19]
	global_load_dwordx4 v[128:131], v87, s[18:19]
	s_add_u32 s18, s18, s17
	s_addc_u32 s19, s19, 0
	global_load_dwordx4 v[132:135], v[34:35], off offset:128
	global_load_dwordx4 v[136:139], v[38:39], off offset:128
	global_load_dwordx4 v[140:143], v84, s[18:19]
	global_load_dwordx4 v[144:147], v85, s[18:19]
	global_load_dwordx4 v[148:151], v86, s[18:19]
	global_load_dwordx4 v[152:155], v87, s[18:19]
	s_add_u32 s18, s18, s101
	s_addc_u32 s19, s19, 0
	global_load_dwordx4 v[156:159], v[34:35], off offset:192
	global_load_dwordx4 v[160:163], v[38:39], off offset:192
	global_load_dwordx4 v[164:167], v84, s[18:19]
	global_load_dwordx4 v[168:171], v85, s[18:19]
	global_load_dwordx4 v[172:175], v86, s[18:19]
	global_load_dwordx4 v[176:179], v87, s[18:19]
	s_add_u32 s18, s18, s17
	s_addc_u32 s19, s19, 0
	global_load_dwordx4 v[180:183], v[34:35], off offset:256
	global_load_dwordx4 v[184:187], v[38:39], off offset:256
	global_load_dwordx4 v[188:191], v84, s[18:19]
	global_load_dwordx4 v[192:195], v85, s[18:19]
	global_load_dwordx4 v[196:199], v86, s[18:19]
	global_load_dwordx4 v[200:203], v87, s[18:19]
	s_add_u32 s18, s18, s101
	s_addc_u32 s19, s19, 0
	s_waitcnt vmcnt(24)
	v_mfma_f32_16x16x32_bf16 v[30:33], v[80:83], v[72:75], 0
	v_mfma_f32_16x16x32_bf16 v[26:29], v[88:91], v[72:75], 0
	v_mfma_f32_16x16x32_bf16 v[22:25], v[92:95], v[72:75], 0
	v_mfma_f32_16x16x32_bf16 v[18:21], v[96:99], v[72:75], 0
	v_mfma_f32_16x16x32_bf16 v[2:5], v[80:83], v[76:79], 0
	v_mfma_f32_16x16x32_bf16 v[6:9], v[88:91], v[76:79], 0
	v_mfma_f32_16x16x32_bf16 v[10:13], v[92:95], v[76:79], 0
	v_mfma_f32_16x16x32_bf16 v[14:17], v[96:99], v[76:79], 0
	global_load_dwordx4 v[72:75], v[34:35], off offset:320
	global_load_dwordx4 v[76:79], v[38:39], off offset:320
	global_load_dwordx4 v[80:83], v84, s[18:19]
	global_load_dwordx4 v[88:91], v85, s[18:19]
	global_load_dwordx4 v[92:95], v86, s[18:19]
	global_load_dwordx4 v[96:99], v87, s[18:19]
	s_add_u32 s18, s18, s17
	s_addc_u32 s19, s19, 0
	s_waitcnt vmcnt(24)
	v_mfma_f32_16x16x32_bf16 v[30:33], v[108:111], v[100:103], v[30:33]
	v_mfma_f32_16x16x32_bf16 v[26:29], v[112:115], v[100:103], v[26:29]
	v_mfma_f32_16x16x32_bf16 v[22:25], v[124:127], v[100:103], v[22:25]
	v_mfma_f32_16x16x32_bf16 v[18:21], v[128:131], v[100:103], v[18:21]
	v_mfma_f32_16x16x32_bf16 v[2:5], v[108:111], v[104:107], v[2:5]
	v_mfma_f32_16x16x32_bf16 v[6:9], v[112:115], v[104:107], v[6:9]
	v_mfma_f32_16x16x32_bf16 v[10:13], v[124:127], v[104:107], v[10:13]
	v_mfma_f32_16x16x32_bf16 v[14:17], v[128:131], v[104:107], v[14:17]
	global_load_dwordx4 v[100:103], v[34:35], off offset:384
	global_load_dwordx4 v[104:107], v[38:39], off offset:384
	global_load_dwordx4 v[108:111], v84, s[18:19]
	global_load_dwordx4 v[112:115], v85, s[18:19]
	global_load_dwordx4 v[124:127], v86, s[18:19]
	global_load_dwordx4 v[128:131], v87, s[18:19]
	s_add_u32 s18, s18, s101
	s_addc_u32 s19, s19, 0
	s_waitcnt vmcnt(24)
	v_mfma_f32_16x16x32_bf16 v[30:33], v[140:143], v[132:135], v[30:33]
	v_mfma_f32_16x16x32_bf16 v[26:29], v[144:147], v[132:135], v[26:29]
	v_mfma_f32_16x16x32_bf16 v[22:25], v[148:151], v[132:135], v[22:25]
	v_mfma_f32_16x16x32_bf16 v[18:21], v[152:155], v[132:135], v[18:21]
	v_mfma_f32_16x16x32_bf16 v[2:5], v[140:143], v[136:139], v[2:5]
	v_mfma_f32_16x16x32_bf16 v[6:9], v[144:147], v[136:139], v[6:9]
	v_mfma_f32_16x16x32_bf16 v[10:13], v[148:151], v[136:139], v[10:13]
	v_mfma_f32_16x16x32_bf16 v[14:17], v[152:155], v[136:139], v[14:17]
	global_load_dwordx4 v[132:135], v[34:35], off offset:448
	global_load_dwordx4 v[136:139], v[38:39], off offset:448
	global_load_dwordx4 v[140:143], v84, s[18:19]
	global_load_dwordx4 v[144:147], v85, s[18:19]
	global_load_dwordx4 v[148:151], v86, s[18:19]
	global_load_dwordx4 v[152:155], v87, s[18:19]
	s_add_u32 s18, s18, s17
	s_addc_u32 s19, s19, 0
	s_waitcnt vmcnt(24)
	v_mfma_f32_16x16x32_bf16 v[30:33], v[164:167], v[156:159], v[30:33]
	v_mfma_f32_16x16x32_bf16 v[26:29], v[168:171], v[156:159], v[26:29]
	v_mfma_f32_16x16x32_bf16 v[22:25], v[172:175], v[156:159], v[22:25]
	v_mfma_f32_16x16x32_bf16 v[18:21], v[176:179], v[156:159], v[18:21]
	v_mfma_f32_16x16x32_bf16 v[2:5], v[164:167], v[160:163], v[2:5]
	v_mfma_f32_16x16x32_bf16 v[6:9], v[168:171], v[160:163], v[6:9]
	v_mfma_f32_16x16x32_bf16 v[10:13], v[172:175], v[160:163], v[10:13]
	v_mfma_f32_16x16x32_bf16 v[14:17], v[176:179], v[160:163], v[14:17]
	global_load_dwordx4 v[156:159], v[34:35], off offset:512
	global_load_dwordx4 v[160:163], v[38:39], off offset:512
	global_load_dwordx4 v[164:167], v84, s[18:19]
	global_load_dwordx4 v[168:171], v85, s[18:19]
	global_load_dwordx4 v[172:175], v86, s[18:19]
	global_load_dwordx4 v[176:179], v87, s[18:19]
	s_add_u32 s18, s18, s101
	s_addc_u32 s19, s19, 0
	s_waitcnt vmcnt(24)
	v_mfma_f32_16x16x32_bf16 v[30:33], v[188:191], v[180:183], v[30:33]
	v_mfma_f32_16x16x32_bf16 v[26:29], v[192:195], v[180:183], v[26:29]
	v_mfma_f32_16x16x32_bf16 v[22:25], v[196:199], v[180:183], v[22:25]
	v_mfma_f32_16x16x32_bf16 v[18:21], v[200:203], v[180:183], v[18:21]
	v_mfma_f32_16x16x32_bf16 v[2:5], v[188:191], v[184:187], v[2:5]
	v_mfma_f32_16x16x32_bf16 v[6:9], v[192:195], v[184:187], v[6:9]
	v_mfma_f32_16x16x32_bf16 v[10:13], v[196:199], v[184:187], v[10:13]
	v_mfma_f32_16x16x32_bf16 v[14:17], v[200:203], v[184:187], v[14:17]
	global_load_dwordx4 v[180:183], v[34:35], off offset:576
	global_load_dwordx4 v[184:187], v[38:39], off offset:576
	global_load_dwordx4 v[188:191], v84, s[18:19]
	global_load_dwordx4 v[192:195], v85, s[18:19]
	global_load_dwordx4 v[196:199], v86, s[18:19]
	global_load_dwordx4 v[200:203], v87, s[18:19]
	s_add_u32 s18, s18, s17
	s_addc_u32 s19, s19, 0
	s_waitcnt vmcnt(24)
	v_mfma_f32_16x16x32_bf16 v[30:33], v[80:83], v[72:75], v[30:33]
	v_mfma_f32_16x16x32_bf16 v[26:29], v[88:91], v[72:75], v[26:29]
	v_mfma_f32_16x16x32_bf16 v[22:25], v[92:95], v[72:75], v[22:25]
	v_mfma_f32_16x16x32_bf16 v[18:21], v[96:99], v[72:75], v[18:21]
	v_mfma_f32_16x16x32_bf16 v[2:5], v[80:83], v[76:79], v[2:5]
	v_mfma_f32_16x16x32_bf16 v[6:9], v[88:91], v[76:79], v[6:9]
	v_mfma_f32_16x16x32_bf16 v[10:13], v[92:95], v[76:79], v[10:13]
	v_mfma_f32_16x16x32_bf16 v[14:17], v[96:99], v[76:79], v[14:17]
	global_load_dwordx4 v[72:75], v[34:35], off offset:640
	global_load_dwordx4 v[76:79], v[38:39], off offset:640
	global_load_dwordx4 v[80:83], v84, s[18:19]
	global_load_dwordx4 v[88:91], v85, s[18:19]
	global_load_dwordx4 v[92:95], v86, s[18:19]
	global_load_dwordx4 v[96:99], v87, s[18:19]
	s_waitcnt vmcnt(24)
	v_mfma_f32_16x16x32_bf16 v[30:33], v[108:111], v[100:103], v[30:33]
	v_mfma_f32_16x16x32_bf16 v[26:29], v[112:115], v[100:103], v[26:29]
	v_mfma_f32_16x16x32_bf16 v[22:25], v[124:127], v[100:103], v[22:25]
	v_mfma_f32_16x16x32_bf16 v[18:21], v[128:131], v[100:103], v[18:21]
	v_mfma_f32_16x16x32_bf16 v[2:5], v[108:111], v[104:107], v[2:5]
	v_mfma_f32_16x16x32_bf16 v[6:9], v[112:115], v[104:107], v[6:9]
	v_mfma_f32_16x16x32_bf16 v[10:13], v[124:127], v[104:107], v[10:13]
	v_mfma_f32_16x16x32_bf16 v[14:17], v[128:131], v[104:107], v[14:17]
	s_waitcnt vmcnt(18)
	v_mfma_f32_16x16x32_bf16 v[30:33], v[140:143], v[132:135], v[30:33]
	v_mfma_f32_16x16x32_bf16 v[26:29], v[144:147], v[132:135], v[26:29]
	v_mfma_f32_16x16x32_bf16 v[22:25], v[148:151], v[132:135], v[22:25]
	v_mfma_f32_16x16x32_bf16 v[18:21], v[152:155], v[132:135], v[18:21]
	v_mfma_f32_16x16x32_bf16 v[2:5], v[140:143], v[136:139], v[2:5]
	v_mfma_f32_16x16x32_bf16 v[6:9], v[144:147], v[136:139], v[6:9]
	v_mfma_f32_16x16x32_bf16 v[10:13], v[148:151], v[136:139], v[10:13]
	v_mfma_f32_16x16x32_bf16 v[14:17], v[152:155], v[136:139], v[14:17]
	s_waitcnt vmcnt(12)
	v_mfma_f32_16x16x32_bf16 v[30:33], v[164:167], v[156:159], v[30:33]
	v_mfma_f32_16x16x32_bf16 v[26:29], v[168:171], v[156:159], v[26:29]
	v_mfma_f32_16x16x32_bf16 v[22:25], v[172:175], v[156:159], v[22:25]
	v_mfma_f32_16x16x32_bf16 v[18:21], v[176:179], v[156:159], v[18:21]
	v_mfma_f32_16x16x32_bf16 v[2:5], v[164:167], v[160:163], v[2:5]
	v_mfma_f32_16x16x32_bf16 v[6:9], v[168:171], v[160:163], v[6:9]
	v_mfma_f32_16x16x32_bf16 v[10:13], v[172:175], v[160:163], v[10:13]
	v_mfma_f32_16x16x32_bf16 v[14:17], v[176:179], v[160:163], v[14:17]
	s_waitcnt vmcnt(6)
	v_mfma_f32_16x16x32_bf16 v[30:33], v[188:191], v[180:183], v[30:33]
	v_mfma_f32_16x16x32_bf16 v[26:29], v[192:195], v[180:183], v[26:29]
	v_mfma_f32_16x16x32_bf16 v[22:25], v[196:199], v[180:183], v[22:25]
	v_mfma_f32_16x16x32_bf16 v[18:21], v[200:203], v[180:183], v[18:21]
	v_mfma_f32_16x16x32_bf16 v[2:5], v[188:191], v[184:187], v[2:5]
	v_mfma_f32_16x16x32_bf16 v[6:9], v[192:195], v[184:187], v[6:9]
	v_mfma_f32_16x16x32_bf16 v[10:13], v[196:199], v[184:187], v[10:13]
	v_mfma_f32_16x16x32_bf16 v[14:17], v[200:203], v[184:187], v[14:17]
	s_waitcnt vmcnt(0)
	v_mfma_f32_16x16x32_bf16 v[30:33], v[80:83], v[72:75], v[30:33]
	v_mfma_f32_16x16x32_bf16 v[26:29], v[88:91], v[72:75], v[26:29]
	v_mfma_f32_16x16x32_bf16 v[22:25], v[92:95], v[72:75], v[22:25]
	v_mfma_f32_16x16x32_bf16 v[18:21], v[96:99], v[72:75], v[18:21]
	v_mfma_f32_16x16x32_bf16 v[2:5], v[80:83], v[76:79], v[2:5]
	v_mfma_f32_16x16x32_bf16 v[6:9], v[88:91], v[76:79], v[6:9]
	v_mfma_f32_16x16x32_bf16 v[10:13], v[92:95], v[76:79], v[10:13]
	v_mfma_f32_16x16x32_bf16 v[14:17], v[96:99], v[76:79], v[14:17]
	v_or_b32_e32 v0, s15, v65
	v_lshlrev_b32_e32 v0, 2, v0
	s_add_i32 s14, s14, s42
	s_add_i32 s13, s13, s68
	s_cmp_ge_i32 s14, s44
	ds_write_b128 v67, v[30:33]
	ds_write_b128 v67, v[26:29] offset:64
	ds_write_b128 v67, v[22:25] offset:128
	s_nop 0
	ds_write_b128 v67, v[18:21] offset:192
	ds_write_b128 v67, v[2:5] offset:4096
	ds_write_b128 v67, v[6:9] offset:4160
	ds_write_b128 v67, v[10:13] offset:4224
	ds_write_b128 v67, v[14:17] offset:4288
	s_waitcnt lgkmcnt(0)
	s_barrier
	ds_read_b128 v[2:5], v66
	v_add_u32_e32 v6, s16, v64
	v_ashrrev_i32_e32 v7, 31, v6
	v_lshlrev_b64 v[6:7], 12, v[6:7]
	v_lshl_add_u64 v[6:7], s[0:1], 0, v[6:7]
	s_waitcnt lgkmcnt(0)
	v_pk_add_f32 v[8:9], v[4:5], 0 op_sel_hi:[1,0]
	v_pk_add_f32 v[10:11], v[2:3], 0 op_sel_hi:[1,0]
	ds_read_b128 v[2:5], v66 offset:8192
	v_lshl_add_u64 v[14:15], v[6:7], 0, v[0:1]
	s_waitcnt lgkmcnt(0)
	v_pk_add_f32 v[8:9], v[8:9], v[4:5]
	v_pk_add_f32 v[10:11], v[10:11], v[2:3]
	ds_read_b128 v[2:5], v66 offset:16384
	s_waitcnt lgkmcnt(0)
	v_pk_add_f32 v[8:9], v[8:9], v[4:5]
	v_pk_add_f32 v[10:11], v[10:11], v[2:3]
	ds_read_b128 v[2:5], v66 offset:24576
	s_waitcnt lgkmcnt(0)
	v_pk_add_f32 v[8:9], v[8:9], v[4:5]
	v_pk_add_f32 v[10:11], v[10:11], v[2:3]
	ds_read_b128 v[2:5], v66 offset:32768
	s_waitcnt lgkmcnt(0)
	v_pk_add_f32 v[8:9], v[8:9], v[4:5]
	v_pk_add_f32 v[10:11], v[10:11], v[2:3]
	ds_read_b128 v[2:5], v66 offset:40960
	s_waitcnt lgkmcnt(0)
	v_pk_add_f32 v[8:9], v[8:9], v[4:5]
	v_pk_add_f32 v[10:11], v[10:11], v[2:3]
	ds_read_b128 v[2:5], v66 offset:49152
	s_waitcnt lgkmcnt(0)
	v_pk_add_f32 v[8:9], v[8:9], v[4:5]
	v_pk_add_f32 v[10:11], v[10:11], v[2:3]
	ds_read_b128 v[2:5], v66 offset:57344
	s_waitcnt lgkmcnt(0)
	v_pk_add_f32 v[12:13], v[8:9], v[4:5]
	v_pk_add_f32 v[10:11], v[10:11], v[2:3]
	global_load_dwordx4 v[2:5], v0, s[8:9]
	global_load_dwordx4 v[6:9], v[14:15], off
	s_waitcnt vmcnt(0)
	v_pk_fma_f32 v[4:5], v[12:13], v[4:5], v[8:9]
	v_pk_fma_f32 v[2:3], v[10:11], v[2:3], v[6:7]
	global_store_dwordx4 v[14:15], v[2:5], off
	s_barrier
	s_cbranch_scc0 .LBB0_1464
